# v10: scan consumer reads each block's 32 coupling scalars with 2 lane-dependent ds_read_b128 + quad_perm broadcast FMAs instead of 8 broadcast reads
# speedup vs baseline: 1.0069x; 1.0069x over previous
; __device__ __forceinline__ void sc_ldb(ScBlk& c, const char* buf, int blk, int arOff, int bkOff, int vOff) {
;   const char* pa = buf + SC_ARA + blk * 512 + arOff; const char* pr = buf + SC_ARR + blk * 512 + arOff;
;   c.aa0 = *(const u32x4*)(pa); c.aa1 = *(const u32x4*)(pa + 64); c.ar0 = *(const u32x4*)(pr); c.ar1 = *(const u32x4*)(pr + 64);
;   const char* bk = buf + SC_BK + blk * 1024 + bkOff;
;   c.k0 = *(const u32x4*)(bk); c.k1 = *(const u32x4*)(bk + 256); c.k2 = *(const u32x4*)(bk + 512); c.k3 = *(const u32x4*)(bk + 768);
;   c.v = *(const f32x4*)(buf + SC_VV + blk * 1024 + vOff);
;   const char* sp = buf + SC_SCAL + blk * 128;
; #pragma unroll
;   for (int i = 0; i < 8; ++i) c.s[i] = *(const f32x4*)(sp + i * 16);
; }
; __device__ void phase_scan(const Params& p, char* lds) {
;     ...
;       for (int c = 0; c < NCH; ++c) {
;         const char* buf = lds + (c & 1) * SC_BUF;
;         char* yb = lds + SC_YB + (c & 1) * 8192 + (cw * 16 + c16) * 16;
;         ScBlk cur; sc_ldb(cur, buf, 0, arOff, bkOff, vOff);
.LBB0_579:
	s_waitcnt lgkmcnt(10)
	v_cndmask_b32_e64 v0, 0, 1, s[22:23]
	s_mov_b32 s24, 0x8400
	v_mul_lo_u32 v86, v0, s24
	s_and_b32 s24, s30, 1
	s_mul_i32 s24, s24, 0x8400
	s_add_i32 s31, s24, 0
	v_add_u32_e32 v223, s31, v205
	v_add_u32_e32 v231, s31, v206
	v_add_u32_e32 v232, s31, v207
	s_waitcnt lgkmcnt(1)
	v_and_b32_e32 v253, 3, v178
	v_lshlrev_b32_e32 v253, 4, v253
	v_add_u32_e32 v34, s31, v253
	v_lshl_add_u32 v175, v0, 13, v207
	ds_read_b128 v[66:69], v223 offset:8192
	ds_read_b128 v[58:61], v223 offset:8256
	ds_read_b128 v[62:65], v223 offset:12288
	ds_read_b128 v[54:57], v223 offset:12352
	ds_read_b128 v[12:15], v231 offset:16384
	ds_read_b128 v[8:11], v231 offset:16640
	ds_read_b128 v[4:7], v231 offset:16896
	ds_read_b128 v[0:3], v231 offset:17152
	ds_read_b128 v[18:21], v232 offset:25600
	ds_read_b128 v[50:53], v34 offset:24576
	ds_read_b128 v[46:49], v34 offset:24640
	v_add_u32_e32 v16, 0x6080, v86
	v_add_u32_e32 v222, v215, v86
	v_add_u32_e32 v233, v216, v86
	v_add_u32_e32 v234, v217, v86
	s_mov_b32 s34, 2
	s_mov_b32 s35, 0
	s_branch .LBB0_581

; __device__ __forceinline__ unsigned cvtpk(float lo, float hi) { f32x2 v = {lo, hi}; bf16x2_t b = __builtin_convertvector(v, bf16x2_t); return *(unsigned*)&b; }
; #define MFMA16(a, b, c) __builtin_amdgcn_mfma_f32_16x16x32_bf16((a), (b), (c), 0, 0, 0)
; __device__ void phase_scan(const Params& p, char* lds) {
;     ...
;         for (int blk = 0; blk < 8; ++blk) {
;           ScBlk nxt; sc_ldb(nxt, buf, (blk + 1) & 7, arOff, bkOff, vOff);
;           u32x4 b1 = {cvtpk(St0[0], St0[1]), cvtpk(St0[2], St0[3]), cvtpk(St1[0], St1[1]), cvtpk(St1[2], St1[3])};
;           u32x4 b2 = {cvtpk(St2[0], St2[1]), cvtpk(St2[2], St2[3]), cvtpk(St3[0], St3[1]), cvtpk(St3[2], St3[3])};
;           f32x4 sr = {0.f, 0.f, 0.f, 0.f}, yr = sr;
;           sr = MFMA16(*(bf16x8*)&cur.aa0, *(bf16x8*)&b1, sr); yr = MFMA16(*(bf16x8*)&cur.ar0, *(bf16x8*)&b1, yr);
;           sr = MFMA16(*(bf16x8*)&cur.aa1, *(bf16x8*)&b2, sr); yr = MFMA16(*(bf16x8*)&cur.ar1, *(bf16x8*)&b2, yr);
;           const float v1 = cur.v[0], v2 = cur.v[1], v3 = cur.v[2], v4 = cur.v[3];
;           const f32x4 s0 = cur.s[0], s1 = cur.s[1], s2 = cur.s[2], s3 = cur.s[3], s4 = cur.s[4], s5 = cur.s[5], s6 = cur.s[6], s7 = cur.s[7];
;           const float sa1 = sr[0];
;           const float sa2 = sr[1] + s0[0] * sa1 + s1[2] * v1;
;           const float sa3 = sr[2] + s0[1] * sa1 + s1[3] * v1 + s0[2] * sa2 + s2[0] * v2;
;           const float sa4 = sr[3] + s0[3] * sa1 + s2[1] * v1 + s1[0] * sa2 + s2[2] * v2 + s1[1] * sa3 + s2[3] * v3;
;           f32x4 y;
;           y[0] = yr[0] + s3[0] * sa1 + s5[2] * v1;
;           y[1] = yr[1] + s3[1] * sa1 + s5[3] * v1 + s3[2] * sa2 + s6[0] * v2;
;           y[2] = yr[2] + s3[3] * sa1 + s6[1] * v1 + s4[0] * sa2 + s6[2] * v2 + s4[1] * sa3 + s6[3] * v3;
;           y[3] = yr[3] + s4[2] * sa1 + s7[0] * v1 + s4[3] * sa2 + s7[1] * v2 + s5[0] * sa3 + s7[2] * v3 + s5[1] * sa4 + s7[3] * v4;
;           u32x4 bu = {cvtpk(sa1, v1), cvtpk(sa2, v2), cvtpk(sa3, v3), cvtpk(sa4, v4)};
;           if (q != 0) { bu[0] = 0u; bu[1] = 0u; bu[2] = 0u; bu[3] = 0u; }
;           St0 = MFMA16(*(bf16x8*)&cur.k0, *(bf16x8*)&bu, St0);
;           St1 = MFMA16(*(bf16x8*)&cur.k1, *(bf16x8*)&bu, St1);
;           St2 = MFMA16(*(bf16x8*)&cur.k2, *(bf16x8*)&bu, St2);
;           St3 = MFMA16(*(bf16x8*)&cur.k3, *(bf16x8*)&bu, St3);
;           *(f32x4*)(yb + blk * 1024) = y;
.LBB0_581:
	v_cvt_pk_bf16_f32 v110, v70, v71
	v_cvt_pk_bf16_f32 v111, v72, v73
	v_cvt_pk_bf16_f32 v112, v74, v75
	v_cvt_pk_bf16_f32 v113, v76, v77
	v_cvt_pk_bf16_f32 v224, v78, v79
	v_cvt_pk_bf16_f32 v225, v80, v81
	s_waitcnt lgkmcnt(10)
	v_mfma_f32_16x16x32_bf16 v[66:69], v[66:69], v[110:113], 0
	v_cvt_pk_bf16_f32 v226, v82, v83
	v_cvt_pk_bf16_f32 v227, v84, v85
	v_add_u32_e32 v86, 0, v234
	s_waitcnt lgkmcnt(8)
	v_mfma_f32_16x16x32_bf16 v[62:65], v[62:65], v[110:113], 0
	v_add_u32_e32 v235, 0, v175
	ds_read_b128 v[236:239], v86
	ds_read_b128 v[240:243], v86 offset:64
	ds_read_b128 v[244:247], v86 offset:4096
	ds_read_b128 v[248:251], v86 offset:4160
	v_add_u32_e32 v86, 0, v233
	v_mfma_f32_16x16x32_bf16 v[58:61], v[58:61], v[224:227], v[66:69]
	v_add_u32_e32 v94, 0, v222
	v_add_u32_e32 v118, v253, v16
	ds_read_b128 v[102:105], v86
	ds_read_b128 v[98:101], v86 offset:256
	ds_read_b128 v[90:93], v86 offset:512
	ds_read_b128 v[86:89], v86 offset:768
	s_waitcnt lgkmcnt(15)
	v_mfma_f32_16x16x32_bf16 v[54:57], v[54:57], v[224:227], v[62:65]
	ds_read_b128 v[94:97], v94
	ds_read_b128 v[134:137], v118
	ds_read_b128 v[130:133], v118 offset:64
	s_waitcnt lgkmcnt(12)
	v_fmac_f32_dpp v59, v50, v58 quad_perm:[0,0,0,0] row_mask:0xf bank_mask:0xf
	v_fmac_f32_dpp v59, v52, v18 quad_perm:[1,1,1,1] row_mask:0xf bank_mask:0xf
	v_fmac_f32_dpp v60, v51, v58 quad_perm:[0,0,0,0] row_mask:0xf bank_mask:0xf
	v_fmac_f32_dpp v60, v53, v18 quad_perm:[1,1,1,1] row_mask:0xf bank_mask:0xf
	v_fmac_f32_dpp v61, v53, v58 quad_perm:[0,0,0,0] row_mask:0xf bank_mask:0xf
	v_fmac_f32_dpp v61, v51, v18 quad_perm:[2,2,2,2] row_mask:0xf bank_mask:0xf
	v_fmac_f32_dpp v60, v52, v59 quad_perm:[0,0,0,0] row_mask:0xf bank_mask:0xf
	v_fmac_f32_dpp v60, v50, v19 quad_perm:[2,2,2,2] row_mask:0xf bank_mask:0xf
	v_fmac_f32_dpp v61, v50, v59 quad_perm:[1,1,1,1] row_mask:0xf bank_mask:0xf
	v_fmac_f32_dpp v61, v52, v19 quad_perm:[2,2,2,2] row_mask:0xf bank_mask:0xf
	v_fmac_f32_dpp v61, v51, v60 quad_perm:[1,1,1,1] row_mask:0xf bank_mask:0xf
	v_fmac_f32_dpp v61, v53, v20 quad_perm:[2,2,2,2] row_mask:0xf bank_mask:0xf
	v_cvt_pk_bf16_f32 v62, v58, v18
	v_cvt_pk_bf16_f32 v63, v59, v19
	v_cvt_pk_bf16_f32 v64, v60, v20
	v_cvt_pk_bf16_f32 v65, v61, v21
	v_cndmask_b32_e64 v38, 0, v62, s[20:21]
	v_cndmask_b32_e64 v39, 0, v63, s[20:21]
	v_cndmask_b32_e64 v40, 0, v64, s[20:21]
	v_cndmask_b32_e64 v41, 0, v65, s[20:21]
	v_fmac_f32_dpp v54, v50, v58 quad_perm:[3,3,3,3] row_mask:0xf bank_mask:0xf
	s_waitcnt lgkmcnt(11)
	v_fmac_f32_dpp v54, v48, v18 quad_perm:[1,1,1,1] row_mask:0xf bank_mask:0xf
	v_mfma_f32_16x16x32_bf16 v[70:73], v[12:15], v[38:41], v[70:73]
	v_fmac_f32_dpp v55, v51, v58 quad_perm:[3,3,3,3] row_mask:0xf bank_mask:0xf
	v_fmac_f32_dpp v55, v49, v18 quad_perm:[1,1,1,1] row_mask:0xf bank_mask:0xf
	v_fmac_f32_dpp v55, v52, v59 quad_perm:[3,3,3,3] row_mask:0xf bank_mask:0xf
	v_fmac_f32_dpp v55, v46, v19 quad_perm:[2,2,2,2] row_mask:0xf bank_mask:0xf
	v_mfma_f32_16x16x32_bf16 v[74:77], v[8:11], v[38:41], v[74:77]
	v_fmac_f32_dpp v56, v53, v58 quad_perm:[3,3,3,3] row_mask:0xf bank_mask:0xf
	v_fmac_f32_dpp v56, v47, v18 quad_perm:[2,2,2,2] row_mask:0xf bank_mask:0xf
	v_fmac_f32_dpp v56, v46, v59 quad_perm:[0,0,0,0] row_mask:0xf bank_mask:0xf
	v_fmac_f32_dpp v56, v48, v19 quad_perm:[2,2,2,2] row_mask:0xf bank_mask:0xf
	v_fmac_f32_dpp v56, v47, v60 quad_perm:[0,0,0,0] row_mask:0xf bank_mask:0xf
	v_fmac_f32_dpp v56, v49, v20 quad_perm:[2,2,2,2] row_mask:0xf bank_mask:0xf
	v_mfma_f32_16x16x32_bf16 v[78:81], v[4:7], v[38:41], v[78:81]
	v_fmac_f32_dpp v57, v48, v58 quad_perm:[0,0,0,0] row_mask:0xf bank_mask:0xf
	v_fmac_f32_dpp v57, v46, v18 quad_perm:[3,3,3,3] row_mask:0xf bank_mask:0xf
	v_fmac_f32_dpp v57, v49, v59 quad_perm:[0,0,0,0] row_mask:0xf bank_mask:0xf
	v_fmac_f32_dpp v57, v47, v19 quad_perm:[3,3,3,3] row_mask:0xf bank_mask:0xf
	v_mfma_f32_16x16x32_bf16 v[82:85], v[0:3], v[38:41], v[82:85]
	v_fmac_f32_dpp v57, v46, v60 quad_perm:[1,1,1,1] row_mask:0xf bank_mask:0xf
	v_fmac_f32_dpp v57, v48, v20 quad_perm:[3,3,3,3] row_mask:0xf bank_mask:0xf
	v_fmac_f32_dpp v57, v47, v61 quad_perm:[1,1,1,1] row_mask:0xf bank_mask:0xf
	v_fmac_f32_dpp v57, v49, v21 quad_perm:[3,3,3,3] row_mask:0xf bank_mask:0xf
	v_add_u32_e32 v0, 0x16800, v235
	ds_write_b128 v0, v[54:57]
	v_cvt_pk_bf16_f32 v26, v70, v71
	v_cvt_pk_bf16_f32 v27, v72, v73
	v_cvt_pk_bf16_f32 v28, v74, v75
	v_cvt_pk_bf16_f32 v29, v76, v77
	v_cvt_pk_bf16_f32 v224, v78, v79
	v_cvt_pk_bf16_f32 v225, v80, v81
	s_waitcnt lgkmcnt(11)
	v_mfma_f32_16x16x32_bf16 v[30:33], v[236:239], v[26:29], 0
	v_cvt_pk_bf16_f32 v226, v82, v83
	v_cvt_pk_bf16_f32 v227, v84, v85
	s_and_b32 s24, s34, 6
	s_waitcnt lgkmcnt(9)
; __device__ void phase_scan(const Params& p, char* lds) {
;     ...
;         for (int blk = 0; blk < 8; ++blk) {
;           ScBlk nxt; sc_ldb(nxt, buf, (blk + 1) & 7, arOff, bkOff, vOff);
;           u32x4 b1 = {cvtpk(St0[0], St0[1]), cvtpk(St0[2], St0[3]), cvtpk(St1[0], St1[1]), cvtpk(St1[2], St1[3])};
;           u32x4 b2 = {cvtpk(St2[0], St2[1]), cvtpk(St2[2], St2[3]), cvtpk(St3[0], St3[1]), cvtpk(St3[2], St3[3])};
;           f32x4 sr = {0.f, 0.f, 0.f, 0.f}, yr = sr;
;           sr = MFMA16(*(bf16x8*)&cur.aa0, *(bf16x8*)&b1, sr); yr = MFMA16(*(bf16x8*)&cur.ar0, *(bf16x8*)&b1, yr);
;           sr = MFMA16(*(bf16x8*)&cur.aa1, *(bf16x8*)&b2, sr); yr = MFMA16(*(bf16x8*)&cur.ar1, *(bf16x8*)&b2, yr);
;           const float v1 = cur.v[0], v2 = cur.v[1], v3 = cur.v[2], v4 = cur.v[3];
;           const f32x4 s0 = cur.s[0], s1 = cur.s[1], s2 = cur.s[2], s3 = cur.s[3], s4 = cur.s[4], s5 = cur.s[5], s6 = cur.s[6], s7 = cur.s[7];
;           const float sa1 = sr[0];
;           const float sa2 = sr[1] + s0[0] * sa1 + s1[2] * v1;
;           const float sa3 = sr[2] + s0[1] * sa1 + s1[3] * v1 + s0[2] * sa2 + s2[0] * v2;
;           const float sa4 = sr[3] + s0[3] * sa1 + s2[1] * v1 + s1[0] * sa2 + s2[2] * v2 + s1[1] * sa3 + s2[3] * v3;
;           f32x4 y;
;           y[0] = yr[0] + s3[0] * sa1 + s5[2] * v1;
;           y[1] = yr[1] + s3[1] * sa1 + s5[3] * v1 + s3[2] * sa2 + s6[0] * v2;
;           y[2] = yr[2] + s3[3] * sa1 + s6[1] * v1 + s4[0] * sa2 + s6[2] * v2 + s4[1] * sa3 + s6[3] * v3;
;           y[3] = yr[3] + s4[2] * sa1 + s7[0] * v1 + s4[3] * sa2 + s7[1] * v2 + s5[0] * sa3 + s7[2] * v3 + s5[1] * sa4 + s7[3] * v4;
;           u32x4 bu = {cvtpk(sa1, v1), cvtpk(sa2, v2), cvtpk(sa3, v3), cvtpk(sa4, v4)};
;           if (q != 0) { bu[0] = 0u; bu[1] = 0u; bu[2] = 0u; bu[3] = 0u; }
;           St0 = MFMA16(*(bf16x8*)&cur.k0, *(bf16x8*)&bu, St0);
;           St1 = MFMA16(*(bf16x8*)&cur.k1, *(bf16x8*)&bu, St1);
;           St2 = MFMA16(*(bf16x8*)&cur.k2, *(bf16x8*)&bu, St2);
;           St3 = MFMA16(*(bf16x8*)&cur.k3, *(bf16x8*)&bu, St3);
;           *(f32x4*)(yb + blk * 1024) = y;
;           cur = nxt;
;           if (blk == 7) {
;             const char* pw = buf + SC_P + 31 * 256 + wOff;
;             St0 *= *(const f32x4*)(pw); St1 *= *(const f32x4*)(pw + 64); St2 *= *(const f32x4*)(pw + 128); St3 *= *(const f32x4*)(pw + 192);
;           }
	v_mfma_f32_16x16x32_bf16 v[236:239], v[244:247], v[26:29], 0
	v_lshl_add_u32 v0, s24, 9, v223
	s_lshl_b32 s25, s24, 10
	s_lshl_b32 s24, s24, 7
	v_mfma_f32_16x16x32_bf16 v[240:243], v[240:243], v[224:227], v[30:33]
	ds_read_b128 v[66:69], v0 offset:8192
	ds_read_b128 v[58:61], v0 offset:8256
	ds_read_b128 v[62:65], v0 offset:12288
	ds_read_b128 v[54:57], v0 offset:12352
	v_add_u32_e32 v0, s25, v231
	v_add_u32_e32 v18, s25, v232
	s_waitcnt lgkmcnt(12)
	v_mfma_f32_16x16x32_bf16 v[224:227], v[248:251], v[224:227], v[236:239]
	s_add_i32 s24, s31, s24
	ds_read_b128 v[12:15], v0 offset:16384
	ds_read_b128 v[8:11], v0 offset:16640
	ds_read_b128 v[4:7], v0 offset:16896
	ds_read_b128 v[0:3], v0 offset:17152
	s_waitcnt lgkmcnt(10)
	v_fmac_f32_dpp v241, v134, v240 quad_perm:[0,0,0,0] row_mask:0xf bank_mask:0xf
	v_fmac_f32_dpp v241, v136, v94 quad_perm:[1,1,1,1] row_mask:0xf bank_mask:0xf
	v_fmac_f32_dpp v242, v135, v240 quad_perm:[0,0,0,0] row_mask:0xf bank_mask:0xf
	v_fmac_f32_dpp v242, v137, v94 quad_perm:[1,1,1,1] row_mask:0xf bank_mask:0xf
	v_fmac_f32_dpp v243, v137, v240 quad_perm:[0,0,0,0] row_mask:0xf bank_mask:0xf
	v_fmac_f32_dpp v243, v135, v94 quad_perm:[2,2,2,2] row_mask:0xf bank_mask:0xf
	v_fmac_f32_dpp v242, v136, v241 quad_perm:[0,0,0,0] row_mask:0xf bank_mask:0xf
	v_fmac_f32_dpp v242, v134, v95 quad_perm:[2,2,2,2] row_mask:0xf bank_mask:0xf
	v_fmac_f32_dpp v243, v134, v241 quad_perm:[1,1,1,1] row_mask:0xf bank_mask:0xf
	v_fmac_f32_dpp v243, v136, v95 quad_perm:[2,2,2,2] row_mask:0xf bank_mask:0xf
	v_fmac_f32_dpp v243, v135, v242 quad_perm:[1,1,1,1] row_mask:0xf bank_mask:0xf
	v_fmac_f32_dpp v243, v137, v96 quad_perm:[2,2,2,2] row_mask:0xf bank_mask:0xf
	v_cvt_pk_bf16_f32 v236, v240, v94
	v_cvt_pk_bf16_f32 v237, v241, v95
	v_cvt_pk_bf16_f32 v238, v242, v96
	v_cvt_pk_bf16_f32 v239, v243, v97
	v_cndmask_b32_e64 v122, 0, v236, s[20:21]
	v_cndmask_b32_e64 v123, 0, v237, s[20:21]
	v_cndmask_b32_e64 v124, 0, v238, s[20:21]
	v_cndmask_b32_e64 v125, 0, v239, s[20:21]
	v_fmac_f32_dpp v224, v134, v240 quad_perm:[3,3,3,3] row_mask:0xf bank_mask:0xf
	s_waitcnt lgkmcnt(9)
	v_fmac_f32_dpp v224, v132, v94 quad_perm:[1,1,1,1] row_mask:0xf bank_mask:0xf
	v_mfma_f32_16x16x32_bf16 v[70:73], v[102:105], v[122:125], v[70:73]
	v_fmac_f32_dpp v225, v135, v240 quad_perm:[3,3,3,3] row_mask:0xf bank_mask:0xf
	v_fmac_f32_dpp v225, v133, v94 quad_perm:[1,1,1,1] row_mask:0xf bank_mask:0xf
	v_fmac_f32_dpp v225, v136, v241 quad_perm:[3,3,3,3] row_mask:0xf bank_mask:0xf
	v_fmac_f32_dpp v225, v130, v95 quad_perm:[2,2,2,2] row_mask:0xf bank_mask:0xf
	v_mfma_f32_16x16x32_bf16 v[74:77], v[98:101], v[122:125], v[74:77]
	v_fmac_f32_dpp v226, v137, v240 quad_perm:[3,3,3,3] row_mask:0xf bank_mask:0xf
	v_fmac_f32_dpp v226, v131, v94 quad_perm:[2,2,2,2] row_mask:0xf bank_mask:0xf
	v_fmac_f32_dpp v226, v130, v241 quad_perm:[0,0,0,0] row_mask:0xf bank_mask:0xf
	v_fmac_f32_dpp v226, v132, v95 quad_perm:[2,2,2,2] row_mask:0xf bank_mask:0xf
	v_fmac_f32_dpp v226, v131, v242 quad_perm:[0,0,0,0] row_mask:0xf bank_mask:0xf
	v_fmac_f32_dpp v226, v133, v96 quad_perm:[2,2,2,2] row_mask:0xf bank_mask:0xf
	v_mfma_f32_16x16x32_bf16 v[78:81], v[90:93], v[122:125], v[78:81]
	v_add_u32_e32 v34, s24, v253
	ds_read_b128 v[18:21], v18 offset:25600
	ds_read_b128 v[50:53], v34 offset:24576
	ds_read_b128 v[46:49], v34 offset:24640
	v_fmac_f32_dpp v227, v132, v240 quad_perm:[0,0,0,0] row_mask:0xf bank_mask:0xf
	v_fmac_f32_dpp v227, v130, v94 quad_perm:[3,3,3,3] row_mask:0xf bank_mask:0xf
	v_fmac_f32_dpp v227, v133, v241 quad_perm:[0,0,0,0] row_mask:0xf bank_mask:0xf
	v_fmac_f32_dpp v227, v131, v95 quad_perm:[3,3,3,3] row_mask:0xf bank_mask:0xf
	v_fmac_f32_dpp v227, v130, v242 quad_perm:[1,1,1,1] row_mask:0xf bank_mask:0xf
	v_fmac_f32_dpp v227, v132, v96 quad_perm:[3,3,3,3] row_mask:0xf bank_mask:0xf
	v_fmac_f32_dpp v227, v131, v243 quad_perm:[1,1,1,1] row_mask:0xf bank_mask:0xf
	v_fmac_f32_dpp v227, v133, v97 quad_perm:[3,3,3,3] row_mask:0xf bank_mask:0xf
	v_mfma_f32_16x16x32_bf16 v[82:85], v[86:89], v[122:125], v[82:85]
	s_cmp_lg_u32 s34, 8
	v_add_u32_e32 v86, 0x16c00, v235
	ds_write_b128 v86, v[224:227]
	s_cbranch_scc1 .LBB0_583
	v_add_u32_e32 v98, s31, v204
	ds_read_b128 v[86:89], v98 offset:7936
	ds_read_b128 v[90:93], v98 offset:8000
	ds_read_b128 v[94:97], v98 offset:8064
	ds_read_b128 v[98:101], v98 offset:8128
	s_waitcnt lgkmcnt(3)
	v_mul_f32_e64 v72, v72, v88
	v_mul_f32_e64 v73, v73, v89
	v_mul_f32_e64 v70, v70, v86
	v_mul_f32_e64 v71, v71, v87
	s_waitcnt lgkmcnt(2)
	v_mul_f32_e64 v76, v76, v92
	v_mul_f32_e64 v77, v77, v93
	v_mul_f32_e64 v74, v74, v90
	v_mul_f32_e64 v75, v75, v91
	s_waitcnt lgkmcnt(1)
	v_mul_f32_e64 v80, v80, v96
	v_mul_f32_e64 v81, v81, v97
	v_mul_f32_e64 v78, v78, v94
	v_mul_f32_e64 v79, v79, v95
	s_waitcnt lgkmcnt(0)
	v_mul_f32_e64 v84, v84, v100
	v_mul_f32_e64 v85, v85, v101
	v_mul_f32_e64 v82, v82, v98
	v_mul_f32_e64 v83, v83, v99
